# prompt diff unit epilogue: 15 subln_g loads hoisted, output stores issued back to back (plus counted vmcnt in prompt loop, sample 2-deep prefetch)
# baseline (speedup 1.0000x reference)
;     ...
;     for (int tt = 0; tt < NT; tt += 2) {
;         if (tt + 2 < NT) DA_ISSUE(pfB, tt + 2);
;         DA_COMPUTE(tt, 0);
;         if (tt + 1 < NT) DA_WRITE(pfA, tt + 1, 1);
;         __syncthreads();
;         if (tt + 1 >= NT) break;
;         if (tt + 3 < NT) DA_ISSUE(pfA, tt + 3);
;         DA_COMPUTE(tt + 1, 1);
;         if (tt + 2 < NT) DA_WRITE(pfB, tt + 2, 0);
.LBB0_931:
	s_and_b64 vcc, exec, s[6:7]
	s_cbranch_vccz .Lp_w1_all
	s_waitcnt vmcnt(4)
	s_branch .Lp_w1_done

;     ...
;     for (int tt = 0; tt < NT; tt += 2) {
;         if (tt + 2 < NT) DA_ISSUE(pfB, tt + 2);
;         DA_COMPUTE(tt, 0);
;         if (tt + 1 < NT) DA_WRITE(pfA, tt + 1, 1);
;         __syncthreads();
;         if (tt + 1 >= NT) break;
;         if (tt + 3 < NT) DA_ISSUE(pfA, tt + 3);
;         DA_COMPUTE(tt + 1, 1);
;         if (tt + 2 < NT) DA_WRITE(pfB, tt + 2, 0);
;         __syncthreads();
.Lp_w1_done:
	s_cmp_ge_u32 s11, s13
	ds_write_b128 v154, v[118:121] offset:38912
	ds_write_b128 v154, v[114:117] offset:38928
	ds_write_b128 v155, v[126:129] offset:57344
	ds_write_b128 v155, v[122:125] offset:57360
	s_waitcnt lgkmcnt(0)
	s_barrier
	s_cbranch_scc1 .LBB0_934
	v_ashrrev_i32_e32 v151, 31, v150
	v_lshlrev_b64 v[66:67], 10, v[150:151]
	v_lshl_or_b32 v66, v148, 1, v66
	v_lshl_add_u64 v[68:69], s[72:73], 0, v[66:67]
	v_lshl_add_u64 v[66:67], s[74:75], 0, v[66:67]
	global_load_dwordx4 v[114:117], v[68:69], off offset:16
	global_load_dwordx4 v[118:121], v[68:69], off
	global_load_dwordx4 v[122:125], v[66:67], off offset:16
	global_load_dwordx4 v[126:129], v[66:67], off
	s_add_i32 s28, s11, -2
	s_cmp_ge_u32 s28, s14
	s_cbranch_scc0 .LBB0_935

;     ...
;         if (tt + 3 < NT) DA_ISSUE(pfA, tt + 3);
;         DA_COMPUTE(tt + 1, 1);
;         if (tt + 2 < NT) DA_WRITE(pfB, tt + 2, 0);
;         __syncthreads();
.LBB0_938:
	s_cmp_ge_u32 s11, s13
	s_cbranch_scc1 .Lp_w2_all
	s_waitcnt vmcnt(4)
	s_branch .Lp_w2_done
.Lp_w2_all:
	s_waitcnt vmcnt(0)
.Lp_w2_done:
	ds_write_b128 v154, v[134:137]
	ds_write_b128 v154, v[130:133] offset:16
	ds_write_b128 v155, v[142:145] offset:18432
	ds_write_b128 v155, v[138:141] offset:18448
	s_branch .LBB0_924

;     ...
;         __syncthreads();
;         if (map == 0) {
;             float ss = 0.f;
; #pragma unroll
;             for (int eb = 0; eb < 4; ++eb)
; #pragma unroll
;                 for (int rg = 0; rg < 16; ++rg) { const float o = OT[eb][rg] * inv - lam * X[(eb * 32 + (rg & 3) + 8 * (rg >> 2) + 4 * hi) * 32 + r]; OT[eb][rg] = o; ss += o * o; }
.LBB0_941:
	s_cmpk_gt_u32 s8, 0xff
	s_waitcnt lgkmcnt(0)
	s_barrier
	s_cbranch_scc1 .LBB0_943
	v_add_u32_e32 v67, 0x400, v66
	ds_read2_b32 v[70:71], v66 offset1:32
	ds_read2_b32 v[72:73], v66 offset0:64 offset1:96
	ds_read2_b32 v[74:75], v67 offset1:32
	ds_read2_b32 v[76:77], v67 offset0:64 offset1:96
	v_add_u32_e32 v67, 0x800, v66
	ds_read2_b32 v[84:85], v67 offset1:32
	ds_read2_b32 v[86:87], v67 offset0:64 offset1:96
	v_add_u32_e32 v67, 0xc00, v66
	ds_read2_b32 v[88:89], v67 offset1:32
	ds_read2_b32 v[90:91], v67 offset0:64 offset1:96
	v_add_u32_e32 v67, 0x1000, v66
	ds_read2_b32 v[92:93], v67 offset1:32
	ds_read2_b32 v[94:95], v67 offset0:64 offset1:96
	v_add_u32_e32 v67, 0x1400, v66
	ds_read2_b32 v[96:97], v67 offset1:32
	ds_read2_b32 v[98:99], v67 offset0:64 offset1:96
	v_add_u32_e32 v67, 0x1800, v66
	s_waitcnt lgkmcnt(11)
	v_pk_mul_f32 v[70:71], v[160:161], v[70:71]
	ds_read2_b32 v[100:101], v67 offset1:32
	ds_read2_b32 v[102:103], v67 offset0:64 offset1:96
	v_add_u32_e32 v67, 0x1c00, v66
	v_pk_fma_f32 v[70:71], v[50:51], v[0:1], v[70:71] op_sel_hi:[1,0,1] neg_lo:[0,0,1] neg_hi:[0,0,1]
	s_waitcnt lgkmcnt(10)
	v_pk_mul_f32 v[50:51], v[160:161], v[76:77]
	ds_read2_b32 v[104:105], v67 offset1:32
	ds_read2_b32 v[106:107], v67 offset0:64 offset1:96
	v_add_u32_e32 v67, 0x2000, v66
	v_pk_mul_f32 v[72:73], v[160:161], v[72:73]
	v_pk_fma_f32 v[50:51], v[56:57], v[0:1], v[50:51] op_sel_hi:[1,0,1] neg_lo:[0,0,1] neg_hi:[0,0,1]
	v_pk_mul_f32 v[56:57], v[160:161], v[74:75]
	ds_read2_b32 v[108:109], v67 offset1:32
	ds_read2_b32 v[110:111], v67 offset0:64 offset1:96
	v_add_u32_e32 v67, 0x2400, v66
	v_pk_fma_f32 v[52:53], v[52:53], v[0:1], v[72:73] op_sel_hi:[1,0,1] neg_lo:[0,0,1] neg_hi:[0,0,1]
	v_pk_fma_f32 v[72:73], v[54:55], v[0:1], v[56:57] op_sel_hi:[1,0,1] neg_lo:[0,0,1] neg_hi:[0,0,1]
	s_waitcnt lgkmcnt(13)
	v_pk_mul_f32 v[56:57], v[160:161], v[84:85]
	ds_read2_b32 v[112:113], v67 offset1:32
	s_waitcnt vmcnt(3)
	ds_read2_b32 v[114:115], v67 offset0:64 offset1:96
	v_add_u32_e32 v67, 0x2800, v66
	v_pk_fma_f32 v[74:75], v[58:59], v[0:1], v[56:57] op_sel_hi:[1,0,1] neg_lo:[0,0,1] neg_hi:[0,0,1]
	s_waitcnt lgkmcnt(13)
	v_pk_mul_f32 v[58:59], v[160:161], v[88:89]
	ds_read2_b32 v[116:117], v67 offset1:32
	s_waitcnt vmcnt(2)
	ds_read2_b32 v[118:119], v67 offset0:64 offset1:96
	v_add_u32_e32 v67, 0x2c00, v66
	v_pk_fma_f32 v[76:77], v[62:63], v[0:1], v[58:59] op_sel_hi:[1,0,1] neg_lo:[0,0,1] neg_hi:[0,0,1]
	s_waitcnt lgkmcnt(12)
	v_pk_mul_f32 v[58:59], v[160:161], v[94:95]
	ds_read2_b32 v[120:121], v67 offset1:32
	s_waitcnt vmcnt(1)
	ds_read2_b32 v[122:123], v67 offset0:64 offset1:96
	v_add_u32_e32 v67, 0x3000, v66
	v_pk_mul_f32 v[54:55], v[160:161], v[86:87]
	v_pk_fma_f32 v[58:59], v[36:37], v[0:1], v[58:59] op_sel_hi:[1,0,1] neg_lo:[0,0,1] neg_hi:[0,0,1]
	v_pk_mul_f32 v[36:37], v[160:161], v[92:93]
	ds_read2_b32 v[124:125], v67 offset1:32
	s_waitcnt vmcnt(0)
	ds_read2_b32 v[126:127], v67 offset0:64 offset1:96
	v_add_u32_e32 v67, 0x3400, v66
	v_add_u32_e32 v78, 0x3800, v66
	v_pk_fma_f32 v[54:55], v[60:61], v[0:1], v[54:55] op_sel_hi:[1,0,1] neg_lo:[0,0,1] neg_hi:[0,0,1]
	v_pk_fma_f32 v[60:61], v[34:35], v[0:1], v[36:37] op_sel_hi:[1,0,1] neg_lo:[0,0,1] neg_hi:[0,0,1]
	s_waitcnt lgkmcnt(14)
	v_pk_mul_f32 v[34:35], v[160:161], v[98:99]
	ds_read2_b32 v[128:129], v67 offset1:32
	ds_read2_b32 v[68:69], v78 offset0:64 offset1:96
	ds_read2_b32 v[130:131], v67 offset0:64 offset1:96
	ds_read2_b32 v[132:133], v78 offset1:32
	v_pk_fma_f32 v[34:35], v[40:41], v[0:1], v[34:35] op_sel_hi:[1,0,1] neg_lo:[0,0,1] neg_hi:[0,0,1]
	s_waitcnt lgkmcnt(14)
	v_pk_mul_f32 v[40:41], v[160:161], v[104:105]
	v_pk_mul_f32 v[36:37], v[160:161], v[96:97]
	v_pk_fma_f32 v[46:47], v[46:47], v[0:1], v[40:41] op_sel_hi:[1,0,1] neg_lo:[0,0,1] neg_hi:[0,0,1]
	s_waitcnt lgkmcnt(12)
	v_pk_mul_f32 v[40:41], v[160:161], v[110:111]
	v_pk_mul_f32 v[56:57], v[160:161], v[90:91]
	v_pk_fma_f32 v[62:63], v[38:39], v[0:1], v[36:37] op_sel_hi:[1,0,1] neg_lo:[0,0,1] neg_hi:[0,0,1]
	v_pk_mul_f32 v[38:39], v[160:161], v[100:101]
	v_pk_fma_f32 v[40:41], v[20:21], v[0:1], v[40:41] op_sel_hi:[1,0,1] neg_lo:[0,0,1] neg_hi:[0,0,1]
	v_pk_mul_f32 v[20:21], v[160:161], v[108:109]
	v_add_u32_e32 v78, 0x3c00, v66
	s_waitcnt lgkmcnt(2)
	v_pk_mul_f32 v[66:67], v[160:161], v[68:69]
	v_pk_fma_f32 v[56:57], v[64:65], v[0:1], v[56:57] op_sel_hi:[1,0,1] neg_lo:[0,0,1] neg_hi:[0,0,1]
	v_pk_mul_f32 v[36:37], v[160:161], v[102:103]
	v_pk_fma_f32 v[64:65], v[42:43], v[0:1], v[38:39] op_sel_hi:[1,0,1] neg_lo:[0,0,1] neg_hi:[0,0,1]
	v_pk_fma_f32 v[42:43], v[18:19], v[0:1], v[20:21] op_sel_hi:[1,0,1] neg_lo:[0,0,1] neg_hi:[0,0,1]
	v_pk_mul_f32 v[18:19], v[160:161], v[114:115]
	v_pk_mul_f32 v[20:21], v[160:161], v[112:113]
	ds_read2_b32 v[80:81], v78 offset1:32
	v_pk_fma_f32 v[66:67], v[12:13], v[0:1], v[66:67] op_sel_hi:[1,0,1] neg_lo:[0,0,1] neg_hi:[0,0,1]
	ds_read2_b32 v[12:13], v78 offset0:64 offset1:96
	v_pk_fma_f32 v[36:37], v[44:45], v[0:1], v[36:37] op_sel_hi:[1,0,1] neg_lo:[0,0,1] neg_hi:[0,0,1]
	v_pk_fma_f32 v[18:19], v[24:25], v[0:1], v[18:19] op_sel_hi:[1,0,1] neg_lo:[0,0,1] neg_hi:[0,0,1]
	v_pk_fma_f32 v[44:45], v[22:23], v[0:1], v[20:21] op_sel_hi:[1,0,1] neg_lo:[0,0,1] neg_hi:[0,0,1]
	v_pk_mul_f32 v[20:21], v[160:161], v[118:119]
	v_pk_mul_f32 v[24:25], v[160:161], v[120:121]
	v_pk_fma_f32 v[20:21], v[28:29], v[0:1], v[20:21] op_sel_hi:[1,0,1] neg_lo:[0,0,1] neg_hi:[0,0,1]
	v_pk_fma_f32 v[28:29], v[30:31], v[0:1], v[24:25] op_sel_hi:[1,0,1] neg_lo:[0,0,1] neg_hi:[0,0,1]
	v_pk_mul_f32 v[24:25], v[160:161], v[126:127]
	v_pk_mul_f32 v[22:23], v[160:161], v[116:117]
	v_pk_fma_f32 v[4:5], v[4:5], v[0:1], v[24:25] op_sel_hi:[1,0,1] neg_lo:[0,0,1] neg_hi:[0,0,1]
	v_pk_mul_f32 v[24:25], v[160:161], v[124:125]
	s_waitcnt lgkmcnt(1)
; #define GASP __attribute__((address_space(1)))
;     ...
;             float ss = 0.f;
; #pragma unroll
;             for (int eb = 0; eb < 4; ++eb)
; #pragma unroll
;                 for (int rg = 0; rg < 16; ++rg) { const float o = OT[eb][rg] * inv - lam * X[(eb * 32 + (rg & 3) + 8 * (rg >> 2) + 4 * hi) * 32 + r]; OT[eb][rg] = o; ss += o * o; }
;             ss += __shfl_xor(ss, 32);
;             const float rms = 0.8f / sqrtf(ss * (1.f / 128.f) + LN_EPS);
;             const float* sg = p.in[16];
;             bf16_t* op = (bf16_t*)(ws + O_MIX) + (size_t)(rowq0 + r) * D + h * 128 + 4 * hi;
; #pragma unroll
;             for (int eb = 0; eb < 4; ++eb)
; #pragma unroll
;                 for (int g4 = 0; g4 < 4; ++g4) { const int e0 = eb * 32 + 8 * g4; const f32x4 gv = *(const GASP f32x4*)(sg + e0 + 4 * hi);
	v_pk_mul_f32 v[68:69], v[160:161], v[80:81]
	v_pk_fma_f32 v[24:25], v[2:3], v[0:1], v[24:25] op_sel_hi:[1,0,1] neg_lo:[0,0,1] neg_hi:[0,0,1]
	v_pk_mul_f32 v[2:3], v[160:161], v[130:131]
	s_waitcnt lgkmcnt(0)
	v_pk_mul_f32 v[12:13], v[160:161], v[12:13]
	v_pk_fma_f32 v[2:3], v[8:9], v[0:1], v[2:3] op_sel_hi:[1,0,1] neg_lo:[0,0,1] neg_hi:[0,0,1]
	v_pk_mul_f32 v[8:9], v[160:161], v[128:129]
	v_pk_mul_f32 v[136:137], v[70:71], v[70:71]
	v_pk_mul_f32 v[38:39], v[160:161], v[106:107]
	v_pk_fma_f32 v[26:27], v[26:27], v[0:1], v[22:23] op_sel_hi:[1,0,1] neg_lo:[0,0,1] neg_hi:[0,0,1]
	v_pk_mul_f32 v[22:23], v[160:161], v[122:123]
	v_pk_fma_f32 v[8:9], v[6:7], v[0:1], v[8:9] op_sel_hi:[1,0,1] neg_lo:[0,0,1] neg_hi:[0,0,1]
	v_pk_mul_f32 v[6:7], v[160:161], v[132:133]
	v_pk_fma_f32 v[68:69], v[14:15], v[0:1], v[68:69] op_sel_hi:[1,0,1] neg_lo:[0,0,1] neg_hi:[0,0,1]
	v_pk_fma_f32 v[16:17], v[16:17], v[0:1], v[12:13] op_sel_hi:[1,0,1] neg_lo:[0,0,1] neg_hi:[0,0,1]
	v_pk_mul_f32 v[134:135], v[52:53], v[52:53]
	v_pk_fma_f32 v[38:39], v[48:49], v[0:1], v[38:39] op_sel_hi:[1,0,1] neg_lo:[0,0,1] neg_hi:[0,0,1]
	v_pk_fma_f32 v[22:23], v[32:33], v[0:1], v[22:23] op_sel_hi:[1,0,1] neg_lo:[0,0,1] neg_hi:[0,0,1]
	v_pk_fma_f32 v[6:7], v[10:11], v[0:1], v[6:7] op_sel_hi:[1,0,1] neg_lo:[0,0,1] neg_hi:[0,0,1]
	v_add_f32_e32 v0, v136, v137
	v_add_f32_e32 v0, v0, v134
	v_pk_mul_f32 v[140:141], v[72:73], v[72:73]
	v_add_f32_e32 v0, v0, v135
	v_add_f32_e32 v0, v0, v140
	v_pk_mul_f32 v[138:139], v[50:51], v[50:51]
	v_add_f32_e32 v0, v0, v141
	v_add_f32_e32 v0, v0, v138
	v_pk_mul_f32 v[84:85], v[74:75], v[74:75]
	v_add_f32_e32 v0, v0, v139
	v_add_f32_e32 v0, v0, v84
	v_pk_mul_f32 v[86:87], v[54:55], v[54:55]
	v_add_f32_e32 v0, v0, v85
	v_add_f32_e32 v0, v0, v86
	v_pk_mul_f32 v[88:89], v[76:77], v[76:77]
	v_add_f32_e32 v0, v0, v87
	v_add_f32_e32 v0, v0, v88
	v_pk_mul_f32 v[90:91], v[56:57], v[56:57]
	v_add_f32_e32 v0, v0, v89
	v_add_f32_e32 v0, v0, v90
	v_pk_mul_f32 v[92:93], v[60:61], v[60:61]
	v_add_f32_e32 v0, v0, v91
	v_add_f32_e32 v0, v0, v92
	v_pk_mul_f32 v[94:95], v[58:59], v[58:59]
	v_add_f32_e32 v0, v0, v93
	v_add_f32_e32 v0, v0, v94
	v_lshlrev_b32_e32 v142, 2, v147
	v_pk_mul_f32 v[96:97], v[62:63], v[62:63]
	v_add_f32_e32 v0, v0, v95
	global_load_dwordx4 v[12:15], v142, s[16:17]
	v_add_f32_e32 v0, v0, v96
	v_pk_mul_f32 v[98:99], v[34:35], v[34:35]
	v_add_f32_e32 v0, v0, v97
	v_add_f32_e32 v0, v0, v98
	v_pk_mul_f32 v[100:101], v[64:65], v[64:65]
	v_add_f32_e32 v0, v0, v99
	v_add_f32_e32 v0, v0, v100
	v_pk_mul_f32 v[102:103], v[36:37], v[36:37]
	v_add_f32_e32 v0, v0, v101
	v_add_f32_e32 v0, v0, v102
	v_pk_mul_f32 v[104:105], v[46:47], v[46:47]
	v_add_f32_e32 v0, v0, v103
	v_add_f32_e32 v0, v0, v104
	v_pk_mul_f32 v[48:49], v[38:39], v[38:39]
	v_add_f32_e32 v0, v0, v105
	v_add_f32_e32 v0, v0, v48
	v_pk_mul_f32 v[108:109], v[42:43], v[42:43]
	v_add_f32_e32 v0, v0, v49
	v_add_f32_e32 v0, v0, v108
	v_pk_mul_f32 v[106:107], v[40:41], v[40:41]
	v_add_f32_e32 v0, v0, v109
	v_add_f32_e32 v0, v0, v106
	v_pk_mul_f32 v[112:113], v[44:45], v[44:45]
	v_add_f32_e32 v0, v0, v107
	v_add_f32_e32 v0, v0, v112
	v_pk_mul_f32 v[110:111], v[18:19], v[18:19]
	v_add_f32_e32 v0, v0, v113
	v_add_f32_e32 v0, v0, v110
	v_pk_mul_f32 v[116:117], v[26:27], v[26:27]
	v_add_f32_e32 v0, v0, v111
	v_add_f32_e32 v0, v0, v116
	v_pk_mul_f32 v[114:115], v[20:21], v[20:21]
	v_add_f32_e32 v0, v0, v117
	v_add_f32_e32 v0, v0, v114
	v_pk_mul_f32 v[30:31], v[28:29], v[28:29]
	v_add_f32_e32 v0, v0, v115
	v_add_f32_e32 v0, v0, v30
	v_pk_mul_f32 v[32:33], v[22:23], v[22:23]
	v_add_f32_e32 v0, v0, v31
	v_add_f32_e32 v0, v0, v32
	v_pk_mul_f32 v[120:121], v[24:25], v[24:25]
	v_add_f32_e32 v0, v0, v33
	v_add_f32_e32 v0, v0, v120
	v_pk_mul_f32 v[118:119], v[4:5], v[4:5]
	v_add_f32_e32 v0, v0, v121
	v_add_f32_e32 v0, v0, v118
	v_pk_mul_f32 v[124:125], v[8:9], v[8:9]
	v_add_f32_e32 v0, v0, v119
	v_add_f32_e32 v0, v0, v124
	v_pk_mul_f32 v[122:123], v[2:3], v[2:3]
	v_add_f32_e32 v0, v0, v125
	v_add_f32_e32 v0, v0, v122
	v_pk_mul_f32 v[10:11], v[6:7], v[6:7]
	v_add_f32_e32 v0, v0, v123
	v_add_f32_e32 v0, v0, v10
	v_pk_mul_f32 v[78:79], v[66:67], v[66:67]
	v_add_f32_e32 v0, v0, v11
	v_add_f32_e32 v0, v0, v78
	v_pk_mul_f32 v[80:81], v[68:69], v[68:69]
	v_add_f32_e32 v0, v0, v79
	v_add_f32_e32 v0, v0, v80
	v_pk_mul_f32 v[82:83], v[16:17], v[16:17]
	v_add_f32_e32 v0, v0, v81
	v_add_f32_e32 v0, v0, v82
	v_add_f32_e32 v0, v0, v83
	ds_bpermute_b32 v10, v171, v0
	global_load_dwordx4 v[80:83], v142, s[16:17] offset:32
	global_load_dwordx4 v[84:87], v142, s[16:17] offset:64
	global_load_dwordx4 v[88:91], v142, s[16:17] offset:96
	global_load_dwordx4 v[92:95], v142, s[16:17] offset:128
	global_load_dwordx4 v[96:99], v142, s[16:17] offset:160
	global_load_dwordx4 v[100:103], v142, s[16:17] offset:192
	global_load_dwordx4 v[104:107], v142, s[16:17] offset:224
	global_load_dwordx4 v[108:111], v142, s[16:17] offset:256
	global_load_dwordx4 v[112:115], v142, s[16:17] offset:288
	global_load_dwordx4 v[116:119], v142, s[16:17] offset:320
	global_load_dwordx4 v[120:123], v142, s[16:17] offset:352
	global_load_dwordx4 v[124:127], v142, s[16:17] offset:384
	global_load_dwordx4 v[128:131], v142, s[16:17] offset:416
	global_load_dwordx4 v[132:135], v142, s[16:17] offset:448
	global_load_dwordx4 v[136:139], v142, s[16:17] offset:480
	s_lshl_b32 s30, s5, 1
	s_waitcnt lgkmcnt(0)
; #define GASP __attribute__((address_space(1)))
;     ...
;             ss += __shfl_xor(ss, 32);
;             const float rms = 0.8f / sqrtf(ss * (1.f / 128.f) + LN_EPS);
;             const float* sg = p.in[16];
;             bf16_t* op = (bf16_t*)(ws + O_MIX) + (size_t)(rowq0 + r) * D + h * 128 + 4 * hi;
; #pragma unroll
;             for (int eb = 0; eb < 4; ++eb)
; #pragma unroll
;                 for (int g4 = 0; g4 < 4; ++g4) { const int e0 = eb * 32 + 8 * g4; const f32x4 gv = *(const GASP f32x4*)(sg + e0 + 4 * hi);
;                     u32x2 w; w.x = pk2(OT[eb][4 * g4] * rms * gv[0], OT[eb][4 * g4 + 1] * rms * gv[1]); w.y = pk2(OT[eb][4 * g4 + 2] * rms * gv[2], OT[eb][4 * g4 + 3] * rms * gv[3]);
;                     *(GASP u32x2*)(op + e0) = w; }
	v_add_f32_e32 v0, v0, v10
	v_fmamk_f32 v0, v0, 0x3c000000, v172
	v_mul_f32_e32 v10, 0x4f800000, v0
	v_cmp_gt_f32_e32 vcc, s35, v0
	s_nop 1
	v_cndmask_b32_e32 v30, v0, v10, vcc
	v_sqrt_f32_e32 v31, v30
	v_lshlrev_b32_e32 v0, 11, v146
	v_lshl_add_u64 v[10:11], s[76:77], 0, v[0:1]
	v_lshl_add_u64 v[10:11], v[10:11], 0, s[30:31]
	v_add_u32_e32 v0, -1, v31
	v_fma_f32 v32, -v0, v31, v30
	v_cmp_ge_f32_e64 s[6:7], 0, v32
	v_add_u32_e32 v32, 1, v31
	s_nop 0
	v_cndmask_b32_e64 v0, v31, v0, s[6:7]
	v_fma_f32 v31, -v32, v31, v30
	v_cmp_lt_f32_e64 s[6:7], 0, v31
	s_nop 1
	v_cndmask_b32_e64 v0, v0, v32, s[6:7]
	v_mul_f32_e32 v31, 0x37800000, v0
	v_cndmask_b32_e32 v0, v0, v31, vcc
	v_cmp_class_f32_e32 vcc, v30, v170
	s_nop 1
	v_cndmask_b32_e32 v32, v0, v30, vcc
	v_div_scale_f32 v33, s[6:7], v32, v32, s1
	v_rcp_f32_e32 v48, v33
	v_lshlrev_b32_e32 v0, 1, v147
	v_lshl_add_u64 v[30:31], v[10:11], 0, v[0:1]
	v_fma_f32 v0, -v33, v48, 1.0
	v_fmac_f32_e32 v48, v0, v48
	v_div_scale_f32 v0, vcc, s1, v32, s1
	v_mul_f32_e32 v10, v0, v48
	v_fma_f32 v11, -v33, v10, v0
	v_fmac_f32_e32 v10, v11, v48
	v_fma_f32 v0, -v33, v10, v0
	v_div_fmas_f32 v0, v0, v48, v10
	v_div_fixup_f32 v0, v0, v32, s1
	v_pk_mul_f32 v[10:11], v[70:71], v[0:1] op_sel_hi:[1,0]
	v_pk_mul_f32 v[32:33], v[54:55], v[0:1] op_sel_hi:[1,0]
	s_waitcnt vmcnt(0)
	v_pk_mul_f32 v[10:11], v[12:13], v[10:11]
	v_pk_mul_f32 v[12:13], v[52:53], v[0:1] op_sel_hi:[1,0]
	v_cvt_pk_bf16_f32 v10, v10, v11
	v_pk_mul_f32 v[12:13], v[14:15], v[12:13]
	v_pk_mul_f32 v[14:15], v[72:73], v[0:1] op_sel_hi:[1,0]
	v_cvt_pk_bf16_f32 v11, v12, v13
	global_store_dwordx2 v[30:31], v[10:11], off
	v_pk_mul_f32 v[18:19], v[18:19], v[0:1] op_sel_hi:[1,0]
	v_pk_mul_f32 v[4:5], v[4:5], v[0:1] op_sel_hi:[1,0]
	v_pk_mul_f32 v[2:3], v[2:3], v[0:1] op_sel_hi:[1,0]
	v_pk_mul_f32 v[6:7], v[6:7], v[0:1] op_sel_hi:[1,0]
	v_pk_mul_f32 v[10:11], v[80:81], v[14:15]
	v_pk_mul_f32 v[14:15], v[50:51], v[0:1] op_sel_hi:[1,0]
	v_cvt_pk_bf16_f32 v10, v10, v11
	v_pk_mul_f32 v[12:13], v[82:83], v[14:15]
	v_pk_mul_f32 v[14:15], v[74:75], v[0:1] op_sel_hi:[1,0]
	v_cvt_pk_bf16_f32 v11, v12, v13
	global_store_dwordx2 v[30:31], v[10:11], off offset:16
	v_pk_mul_f32 v[10:11], v[84:85], v[14:15]
	v_pk_mul_f32 v[12:13], v[86:87], v[32:33]
	v_cvt_pk_bf16_f32 v10, v10, v11
	v_cvt_pk_bf16_f32 v11, v12, v13
	global_store_dwordx2 v[30:31], v[10:11], off offset:32
	v_pk_mul_f32 v[14:15], v[76:77], v[0:1] op_sel_hi:[1,0]
	v_pk_mul_f32 v[32:33], v[56:57], v[0:1] op_sel_hi:[1,0]
	v_pk_mul_f32 v[10:11], v[88:89], v[14:15]
	v_pk_mul_f32 v[12:13], v[90:91], v[32:33]
	v_cvt_pk_bf16_f32 v10, v10, v11
	v_cvt_pk_bf16_f32 v11, v12, v13
	global_store_dwordx2 v[30:31], v[10:11], off offset:48
	v_pk_mul_f32 v[14:15], v[60:61], v[0:1] op_sel_hi:[1,0]
	v_pk_mul_f32 v[32:33], v[58:59], v[0:1] op_sel_hi:[1,0]
	v_pk_mul_f32 v[10:11], v[14:15], v[92:93]
	v_pk_mul_f32 v[12:13], v[32:33], v[94:95]
	v_cvt_pk_bf16_f32 v10, v10, v11
	v_cvt_pk_bf16_f32 v11, v12, v13
	global_store_dwordx2 v[30:31], v[10:11], off offset:64
	v_pk_mul_f32 v[14:15], v[62:63], v[0:1] op_sel_hi:[1,0]
	v_pk_mul_f32 v[32:33], v[34:35], v[0:1] op_sel_hi:[1,0]
	v_pk_mul_f32 v[10:11], v[14:15], v[96:97]
	v_pk_mul_f32 v[12:13], v[32:33], v[98:99]
	v_cvt_pk_bf16_f32 v10, v10, v11
	v_cvt_pk_bf16_f32 v11, v12, v13
	global_store_dwordx2 v[30:31], v[10:11], off offset:80
	v_pk_mul_f32 v[14:15], v[64:65], v[0:1] op_sel_hi:[1,0]
	v_pk_mul_f32 v[32:33], v[36:37], v[0:1] op_sel_hi:[1,0]
	v_pk_mul_f32 v[10:11], v[14:15], v[100:101]
	v_pk_mul_f32 v[12:13], v[32:33], v[102:103]
	v_cvt_pk_bf16_f32 v10, v10, v11
	v_cvt_pk_bf16_f32 v11, v12, v13
	global_store_dwordx2 v[30:31], v[10:11], off offset:96
	v_pk_mul_f32 v[14:15], v[46:47], v[0:1] op_sel_hi:[1,0]
	v_pk_mul_f32 v[32:33], v[38:39], v[0:1] op_sel_hi:[1,0]
	v_pk_mul_f32 v[10:11], v[14:15], v[104:105]
	v_pk_mul_f32 v[12:13], v[32:33], v[106:107]
	v_cvt_pk_bf16_f32 v10, v10, v11
	v_cvt_pk_bf16_f32 v11, v12, v13
	global_store_dwordx2 v[30:31], v[10:11], off offset:112
	v_pk_mul_f32 v[14:15], v[42:43], v[0:1] op_sel_hi:[1,0]
	v_pk_mul_f32 v[32:33], v[40:41], v[0:1] op_sel_hi:[1,0]
	v_pk_mul_f32 v[10:11], v[14:15], v[108:109]
	v_pk_mul_f32 v[12:13], v[32:33], v[110:111]
	v_cvt_pk_bf16_f32 v10, v10, v11
	v_cvt_pk_bf16_f32 v11, v12, v13
	global_store_dwordx2 v[30:31], v[10:11], off offset:128
	v_pk_mul_f32 v[14:15], v[44:45], v[0:1] op_sel_hi:[1,0]
	v_pk_mul_f32 v[12:13], v[18:19], v[114:115]
	v_pk_mul_f32 v[10:11], v[14:15], v[112:113]
	v_pk_mul_f32 v[14:15], v[26:27], v[0:1] op_sel_hi:[1,0]
	v_cvt_pk_bf16_f32 v10, v10, v11
	v_cvt_pk_bf16_f32 v11, v12, v13
	global_store_dwordx2 v[30:31], v[10:11], off offset:144
	v_pk_mul_f32 v[18:19], v[20:21], v[0:1] op_sel_hi:[1,0]
	v_pk_mul_f32 v[10:11], v[14:15], v[116:117]
	v_pk_mul_f32 v[12:13], v[18:19], v[118:119]
	v_cvt_pk_bf16_f32 v10, v10, v11
	v_cvt_pk_bf16_f32 v11, v12, v13
	global_store_dwordx2 v[30:31], v[10:11], off offset:160
	v_pk_mul_f32 v[14:15], v[28:29], v[0:1] op_sel_hi:[1,0]
	v_pk_mul_f32 v[18:19], v[22:23], v[0:1] op_sel_hi:[1,0]
	v_pk_mul_f32 v[10:11], v[14:15], v[120:121]
	v_pk_mul_f32 v[12:13], v[18:19], v[122:123]
	v_cvt_pk_bf16_f32 v10, v10, v11
	v_cvt_pk_bf16_f32 v11, v12, v13
	global_store_dwordx2 v[30:31], v[10:11], off offset:176
	v_pk_mul_f32 v[14:15], v[24:25], v[0:1] op_sel_hi:[1,0]
	v_pk_mul_f32 v[4:5], v[4:5], v[126:127]
	v_pk_mul_f32 v[10:11], v[14:15], v[124:125]
	s_nop 0
	v_cvt_pk_bf16_f32 v10, v10, v11
	v_cvt_pk_bf16_f32 v11, v4, v5
	global_store_dwordx2 v[30:31], v[10:11], off offset:192
	v_pk_mul_f32 v[4:5], v[8:9], v[0:1] op_sel_hi:[1,0]
	v_pk_mul_f32 v[8:9], v[66:67], v[0:1] op_sel_hi:[1,0]
	v_pk_mul_f32 v[4:5], v[4:5], v[128:129]
	v_pk_mul_f32 v[2:3], v[2:3], v[130:131]
	v_cvt_pk_bf16_f32 v4, v4, v5
	v_cvt_pk_bf16_f32 v5, v2, v3
	global_store_dwordx2 v[30:31], v[4:5], off offset:208
	v_pk_mul_f32 v[2:3], v[6:7], v[132:133]
	v_pk_mul_f32 v[4:5], v[8:9], v[134:135]
	v_cvt_pk_bf16_f32 v2, v2, v3
	v_cvt_pk_bf16_f32 v3, v4, v5
	global_store_dwordx2 v[30:31], v[2:3], off offset:224
	v_pk_mul_f32 v[6:7], v[68:69], v[0:1] op_sel_hi:[1,0]
	v_pk_mul_f32 v[8:9], v[16:17], v[0:1] op_sel_hi:[1,0]
	v_pk_mul_f32 v[2:3], v[6:7], v[136:137]
	v_pk_mul_f32 v[4:5], v[8:9], v[138:139]
	v_cvt_pk_bf16_f32 v2, v2, v3
	v_cvt_pk_bf16_f32 v3, v4, v5
	global_store_dwordx2 v[30:31], v[2:3], off offset:240
